# grid barrier: agent-scope cache invalidate issued at arrival (overlaps the wait) instead of after the release is observed
# speedup vs baseline: 1.0342x; 1.0055x over previous
.LBB0_54:
	s_mov_b64 s[8:9], exec
	v_readlane_b32 s3, v248, 4
	s_lshl_b32 s3, s3, 8
	v_readlane_b32 s6, v248, 2
	v_mbcnt_lo_u32_b32 v1, s8, 0
	v_readlane_b32 s7, v248, 3
	s_add_u32 s6, s6, s3
	v_mbcnt_hi_u32_b32 v1, s9, v1
	s_addc_u32 s7, s7, 0
	v_cmp_eq_u32_e32 vcc, 0, v1
	s_and_saveexec_b64 s[10:11], vcc
	s_cbranch_execz .LBB0_56
	s_bcnt1_i32_b64 s3, s[8:9]
	v_mov_b32_e32 v3, 0x1000
	v_mov_b32_e32 v4, s3
	global_atomic_add v3, v3, v4, s[6:7] offset:1024 sc0
	buffer_inv sc1

.LBB0_69:
	s_or_b64 exec, exec, s[10:11]
	s_waitcnt vmcnt(0)
	s_waitcnt vmcnt(0)

.LBB0_87:
	s_or_b64 exec, exec, s[8:9]
	s_mov_b64 s[8:9], exec
	v_mbcnt_lo_u32_b32 v0, s8, 0
	v_mbcnt_hi_u32_b32 v0, s9, v0
	v_cmp_eq_u32_e32 vcc, 0, v0
	s_waitcnt vmcnt(0)
	s_and_saveexec_b64 s[10:11], vcc
	s_cbranch_execz .LBB0_89
	s_bcnt1_i32_b64 s3, s[8:9]
	v_mov_b32_e32 v0, 0x2000
	v_mov_b32_e32 v1, s3
	global_atomic_add v0, v1, s[6:7] offset:1024

.LBB0_374:
	s_mov_b64 s[8:9], exec
	v_readlane_b32 s6, v248, 4
	s_lshl_b32 s6, s6, 8
	v_readlane_b32 s10, v248, 2
	v_mbcnt_lo_u32_b32 v1, s8, 0
	v_readlane_b32 s11, v248, 3
	s_add_u32 s6, s10, s6
	v_mbcnt_hi_u32_b32 v1, s9, v1
	s_addc_u32 s7, s11, 0
	v_cmp_eq_u32_e32 vcc, 0, v1
	s_and_saveexec_b64 s[10:11], vcc
	s_cbranch_execz .LBB0_376
	s_bcnt1_i32_b64 s8, s[8:9]
	v_mov_b32_e32 v3, 0x1000
	v_mov_b32_e32 v4, s8
	global_atomic_add v3, v3, v4, s[6:7] offset:1024 sc0
	buffer_inv sc1

.LBB0_407:
	s_or_b64 exec, exec, s[8:9]
	s_mov_b64 s[8:9], exec
	v_mbcnt_lo_u32_b32 v0, s8, 0
	v_mbcnt_hi_u32_b32 v0, s9, v0
	v_cmp_eq_u32_e32 vcc, 0, v0
	s_waitcnt vmcnt(0)
	s_and_saveexec_b64 s[10:11], vcc
	s_cbranch_execz .LBB0_409
	s_bcnt1_i32_b64 s8, s[8:9]
	v_mov_b32_e32 v0, 0x2000
	v_mov_b32_e32 v1, s8
	global_atomic_add v0, v1, s[6:7] offset:1024

.LBB0_611:
	s_mov_b64 s[10:11], exec
	v_readlane_b32 s8, v248, 4
	s_lshl_b32 s8, s8, 8
	v_readlane_b32 s12, v248, 2
	v_mbcnt_lo_u32_b32 v1, s10, 0
	v_readlane_b32 s13, v248, 3
	s_add_u32 s8, s12, s8
	v_mbcnt_hi_u32_b32 v1, s11, v1
	s_addc_u32 s9, s13, 0
	v_cmp_eq_u32_e32 vcc, 0, v1
	s_and_saveexec_b64 s[12:13], vcc
	s_cbranch_execz .LBB0_613
	s_bcnt1_i32_b64 s10, s[10:11]
	v_mov_b32_e32 v3, 0x1000
	v_mov_b32_e32 v4, s10
	global_atomic_add v3, v3, v4, s[8:9] offset:1024 sc0
	buffer_inv sc1

.LBB0_626:
	s_or_b64 exec, exec, s[12:13]
	s_waitcnt vmcnt(0)
	s_waitcnt vmcnt(0)

.LBB0_644:
	s_or_b64 exec, exec, s[10:11]
	s_mov_b64 s[10:11], exec
	v_mbcnt_lo_u32_b32 v0, s10, 0
	v_mbcnt_hi_u32_b32 v0, s11, v0
	v_cmp_eq_u32_e32 vcc, 0, v0
	s_waitcnt vmcnt(0)
	s_and_saveexec_b64 s[12:13], vcc
	s_cbranch_execz .LBB0_646
	s_bcnt1_i32_b64 s10, s[10:11]
	v_mov_b32_e32 v0, 0x2000
	v_mov_b32_e32 v1, s10
	global_atomic_add v0, v1, s[8:9] offset:1024

.LBB0_792:
	s_mov_b64 s[12:13], exec
	v_readlane_b32 s10, v248, 4
	s_lshl_b32 s10, s10, 8
	v_readlane_b32 s14, v248, 2
	v_mbcnt_lo_u32_b32 v1, s12, 0
	v_readlane_b32 s15, v248, 3
	s_add_u32 s10, s14, s10
	v_mbcnt_hi_u32_b32 v1, s13, v1
	s_addc_u32 s11, s15, 0
	v_cmp_eq_u32_e32 vcc, 0, v1
	s_and_saveexec_b64 s[16:17], vcc
	s_cbranch_execz .LBB0_794
	s_bcnt1_i32_b64 s12, s[12:13]
	v_mov_b32_e32 v3, 0x1000
	v_mov_b32_e32 v4, s12
	global_atomic_add v3, v3, v4, s[10:11] offset:1024 sc0
	buffer_inv sc1

.LBB0_807:
	s_or_b64 exec, exec, s[16:17]
	s_waitcnt vmcnt(0)
	s_waitcnt vmcnt(0)

.LBB0_825:
	s_or_b64 exec, exec, s[12:13]
	s_mov_b64 s[12:13], exec
	v_mbcnt_lo_u32_b32 v0, s12, 0
	v_mbcnt_hi_u32_b32 v0, s13, v0
	v_cmp_eq_u32_e32 vcc, 0, v0
	s_waitcnt vmcnt(0)
	s_and_saveexec_b64 s[16:17], vcc
	s_cbranch_execz .LBB0_827
	s_bcnt1_i32_b64 s12, s[12:13]
	v_mov_b32_e32 v0, 0x2000
	v_mov_b32_e32 v1, s12
	global_atomic_add v0, v1, s[10:11] offset:1024
